# prompt attention PV: V-fragment LDS reads issued after the max exchange, before the exps
# speedup vs baseline: 1.0039x; 1.0039x over previous
; #define LAS __attribute__((address_space(3)))
; __device__ __forceinline__ float xor16_get(float v) { return __builtin_bit_cast(float, __builtin_amdgcn_ds_swizzle(__builtin_bit_cast(int, v), 0x401F)); }
; __device__ __forceinline__ float xor32_max(float v) { const unsigned u = __builtin_bit_cast(unsigned, v); auto r = __builtin_amdgcn_permlane32_swap(u, u, false, false); return fmaxf(__builtin_bit_cast(float, (unsigned)r[0]), __builtin_bit_cast(float, (unsigned)r[1])); }
; __device__ __forceinline__ f32x4 mfma16(bf16x8 a, bf16x8 b, f32x4 c) { return __builtin_amdgcn_mfma_f32_16x16x32_bf16(a, b, c, 0, 0, 0); }
; __device__ __forceinline__ void attn_prompt_unit(const PP P, LAS unsigned char* lds, int b, int h, int qt) {
;     ...
;     for (int kt = 0; kt < nt_blk; ++kt) {
;         const bool more = kt + 1 < nt_blk;
;         if (more) { rk = *(const u32x4*)(gk + (size_t)(kt + 1) * 64 * 512); rv = *(const u32x4*)(gv + (kt + 1) * 64); if (tid < 256) rp = *(const u32x4*)(gp + (size_t)(kt + 1) * 64 * 32); }
;         if (kt < nt_w) {
;             const LAS unsigned char* kb = lds + (kt & 1) * AT_STAGE; const LAS unsigned char* vb = kb + AT_V;
;             f32x4 s[2][4];
; #pragma unroll
;             for (int sb = 0; sb < 4; ++sb) { s[0][sb] = (f32x4){0.f, 0.f, 0.f, 0.f}; s[1][sb] = (f32x4){0.f, 0.f, 0.f, 0.f};
; #pragma unroll
;                 for (int ks = 0; ks < 3; ++ks) { const bf16x8 kf = *(const LAS bf16x8*)(kb + (16 * sb + fr) * AT_KROW + ks * 64 + fq * 16);
;                     s[0][sb] = mfma16(kf, Qb[0][ks], s[0][sb]); s[1][sb] = mfma16(kf, Qb[1][ks], s[1][sb]); } }
;             bf16x8 Pb[2][2];
; #pragma unroll
;             for (int g = 0; g < 2; ++g) {
;                 float mx = -INFINITY;
; #pragma unroll
;                 for (int sb = 0; sb < 4; ++sb) mx = fmaxf(mx, fmaxf(fmaxf(s[g][sb][0], s[g][sb][1]), fmaxf(s[g][sb][2], s[g][sb][3])));
;                 mx = fmaxf(mx, xor16_get(mx)); mx = xor32_max(mx);
;                 const float mnew = fmaxf(m[g], mx), alpha = __builtin_amdgcn_exp2f(m[g] - mnew); m[g] = mnew;
;                 float ps = 0.f; float p[4][4];
; #pragma unroll
;                 for (int sb = 0; sb < 4; ++sb)
; #pragma unroll
;                     for (int j = 0; j < 4; ++j) { p[sb][j] = __builtin_amdgcn_exp2f(s[g][sb][j] - mnew); ps += p[sb][j]; }
.LBB0_44:
	s_or_b64 exec, exec, s[2:3]
	v_cmp_le_i32_e32 vcc, s26, v121
	s_and_saveexec_b64 s[2:3], vcc
	s_cbranch_execz .LBB0_46
	s_bitcmp1_b32 s26, 0
	s_cselect_b32 s27, 0x5800, 0
	s_add_i32 s27, s27, 0
	v_add3_u32 v73, s27, v98, v147
	ds_read_b128 v[200:203], v73
	ds_read_b128 v[204:207], v73 offset:64
	ds_read_b128 v[208:211], v73 offset:128
	ds_read_b128 v[212:215], v73 offset:3328
	ds_read_b128 v[216:219], v73 offset:3392
	ds_read_b128 v[220:223], v73 offset:3456
	ds_read_b128 v[224:227], v73 offset:6656
	ds_read_b128 v[228:231], v73 offset:6720
	ds_read_b128 v[232:235], v73 offset:6784
	ds_read_b128 v[236:239], v73 offset:9984
	ds_read_b128 v[240:243], v73 offset:10048
	ds_read_b128 v[244:247], v73 offset:10112
	s_waitcnt lgkmcnt(11)
	v_mfma_f32_16x16x32_bf16 v[154:157], v[200:203], v[40:43], 0
	v_mfma_f32_16x16x32_bf16 v[80:83], v[200:203], v[28:31], 0
	s_waitcnt lgkmcnt(10)
	v_mfma_f32_16x16x32_bf16 v[154:157], v[204:207], v[36:39], v[154:157]
	v_mfma_f32_16x16x32_bf16 v[80:83], v[204:207], v[20:23], v[80:83]
	s_waitcnt lgkmcnt(9)
	v_mfma_f32_16x16x32_bf16 v[154:157], v[208:211], v[32:35], v[154:157]
	v_mfma_f32_16x16x32_bf16 v[80:83], v[208:211], v[16:19], v[80:83]
	s_waitcnt lgkmcnt(8)
	v_mfma_f32_16x16x32_bf16 v[158:161], v[212:215], v[40:43], 0
	v_mfma_f32_16x16x32_bf16 v[84:87], v[212:215], v[28:31], 0
	s_waitcnt lgkmcnt(7)
	v_mfma_f32_16x16x32_bf16 v[158:161], v[216:219], v[36:39], v[158:161]
	v_mfma_f32_16x16x32_bf16 v[84:87], v[216:219], v[20:23], v[84:87]
	s_waitcnt lgkmcnt(6)
	v_mfma_f32_16x16x32_bf16 v[158:161], v[220:223], v[32:35], v[158:161]
	v_mfma_f32_16x16x32_bf16 v[84:87], v[220:223], v[16:19], v[84:87]
	s_waitcnt lgkmcnt(5)
	v_mfma_f32_16x16x32_bf16 v[178:181], v[224:227], v[40:43], 0
	v_mfma_f32_16x16x32_bf16 v[88:91], v[224:227], v[28:31], 0
	s_waitcnt lgkmcnt(4)
	v_mfma_f32_16x16x32_bf16 v[178:181], v[228:231], v[36:39], v[178:181]
	v_mfma_f32_16x16x32_bf16 v[88:91], v[228:231], v[20:23], v[88:91]
	s_waitcnt lgkmcnt(3)
	v_mfma_f32_16x16x32_bf16 v[178:181], v[232:235], v[32:35], v[178:181]
	v_mfma_f32_16x16x32_bf16 v[88:91], v[232:235], v[16:19], v[88:91]
	s_waitcnt lgkmcnt(2)
	v_mfma_f32_16x16x32_bf16 v[182:185], v[236:239], v[40:43], 0
	v_mfma_f32_16x16x32_bf16 v[92:95], v[236:239], v[28:31], 0
	s_waitcnt lgkmcnt(1)
	v_mfma_f32_16x16x32_bf16 v[182:185], v[240:243], v[36:39], v[182:185]
	v_mfma_f32_16x16x32_bf16 v[92:95], v[240:243], v[20:23], v[92:95]
	s_waitcnt lgkmcnt(0)
	v_mfma_f32_16x16x32_bf16 v[182:185], v[244:247], v[32:35], v[182:185]
	v_mfma_f32_16x16x32_bf16 v[92:95], v[244:247], v[16:19], v[92:95]
	s_nop 7
	s_nop 1
	v_max_f32_e32 v125, v83, v83
	v_max_f32_e32 v73, v157, v157
	v_max_f32_e32 v139, v86, v86
	s_nop 1
	v_max_f32_e32 v74, v156, v156
	v_max_f32_e32 v73, v74, v73
	v_max_f32_e32 v74, v161, v161
	v_max_f32_e32 v75, v160, v160
	v_max_f32_e32 v74, v75, v74
	v_max3_f32 v73, v154, v155, v73
	v_max3_f32 v74, v158, v159, v74
	v_max3_f32 v73, v73, s37, v74
	v_max_f32_e32 v74, v181, v181
	v_max_f32_e32 v75, v180, v180
	v_max_f32_e32 v74, v75, v74
	v_max_f32_e32 v75, v185, v185
	v_max_f32_e32 v76, v184, v184
	v_max_f32_e32 v75, v76, v75
	v_max3_f32 v74, v178, v179, v74
	v_max3_f32 v75, v182, v183, v75
	v_max3_f32 v73, v73, v74, v75
	ds_swizzle_b32 v74, v73 offset:swizzle(SWAP,16)
	v_max_f32_e32 v141, v94, v94
	s_waitcnt lgkmcnt(0)
	v_max_f32_e32 v74, v74, v74
	v_max_f32_e32 v73, v73, v74
	v_mov_b32_e32 v74, v73
	s_nop 1
	v_permlane32_swap_b32_e32 v73, v74
	v_max3_f32 v123, v72, v73, v74
	v_sub_f32_e32 v72, v72, v123
	v_exp_f32_e32 v136, v72
	v_sub_f32_e32 v72, v154, v123
	v_exp_f32_e32 v138, v72
	v_sub_f32_e32 v72, v155, v123
	v_pk_mul_f32 v[46:47], v[46:47], v[136:137] op_sel_hi:[1,0]
	v_pk_mul_f32 v[44:45], v[44:45], v[136:137] op_sel_hi:[1,0]
	v_pk_mul_f32 v[54:55], v[54:55], v[136:137] op_sel_hi:[1,0]
	v_pk_mul_f32 v[52:53], v[52:53], v[136:137] op_sel_hi:[1,0]
	v_pk_mul_f32 v[58:59], v[58:59], v[136:137] op_sel_hi:[1,0]
	v_pk_mul_f32 v[56:57], v[56:57], v[136:137] op_sel_hi:[1,0]
	v_pk_mul_f32 v[70:71], v[70:71], v[136:137] op_sel_hi:[1,0]
	v_pk_mul_f32 v[68:69], v[68:69], v[136:137] op_sel_hi:[1,0]
	v_max_f32_e32 v137, v82, v82
	v_max_f32_e32 v125, v137, v125
	v_max_f32_e32 v137, v87, v87
	v_max_f32_e32 v137, v139, v137
	v_max3_f32 v125, v80, v81, v125
	v_max3_f32 v137, v84, v85, v137
	v_max3_f32 v125, v125, s37, v137
	v_max_f32_e32 v137, v91, v91
	v_max_f32_e32 v139, v90, v90
	v_max_f32_e32 v137, v139, v137
	v_max_f32_e32 v139, v95, v95
	v_max_f32_e32 v139, v141, v139
	v_max3_f32 v137, v88, v89, v137
	v_max3_f32 v139, v92, v93, v139
	v_max3_f32 v125, v125, v137, v139
	ds_swizzle_b32 v137, v125 offset:swizzle(SWAP,16)
	v_exp_f32_e32 v140, v72
	v_sub_f32_e32 v72, v156, v123
	v_exp_f32_e32 v154, v72
	v_sub_f32_e32 v72, v157, v123
	s_waitcnt lgkmcnt(0)
; #define LAS __attribute__((address_space(3)))
; __device__ __forceinline__ unsigned pk2(float lo, float hi) { const f32x2_ v = {lo, hi}; return __builtin_bit_cast(unsigned, __builtin_convertvector(v, bf16x2_)); }
; __device__ __forceinline__ f32x4 mfma16(bf16x8 a, bf16x8 b, f32x4 c) { return __builtin_amdgcn_mfma_f32_16x16x32_bf16(a, b, c, 0, 0, 0); }
; __device__ __forceinline__ void attn_prompt_unit(const PP P, LAS unsigned char* lds, int b, int h, int qt) {
;     ...
;                 const float mnew = fmaxf(m[g], mx), alpha = __builtin_amdgcn_exp2f(m[g] - mnew); m[g] = mnew;
;                 float ps = 0.f; float p[4][4];
; #pragma unroll
;                 for (int sb = 0; sb < 4; ++sb)
; #pragma unroll
;                     for (int j = 0; j < 4; ++j) { p[sb][j] = __builtin_amdgcn_exp2f(s[g][sb][j] - mnew); ps += p[sb][j]; }
;                 lsum[g] = lsum[g] * alpha + ps;
; #pragma unroll
;                 for (int kk = 0; kk < 2; ++kk) { u32x4 pw; pw.x = pk2(p[2 * kk][0], p[2 * kk][1]); pw.y = pk2(p[2 * kk][2], p[2 * kk][3]); pw.z = pk2(p[2 * kk + 1][0], p[2 * kk + 1][1]); pw.w = pk2(p[2 * kk + 1][2], p[2 * kk + 1][3]);
;                     Pb[g][kk] = __builtin_bit_cast(bf16x8, pw); }
; #pragma unroll
;                 for (int nt = 0; nt < 4; ++nt) O[g][nt] = O[g][nt] * alpha;
;             }
; #pragma unroll
;             for (int nt = 0; nt < 4; ++nt)
; #pragma unroll
;                 for (int kk = 0; kk < 2; ++kk) { const LAS unsigned char* vp = vb + (16 * nt + fr) * AT_VROW + kk * 64 + fq * 8;
;                     const s16x4 a = *(const LAS s16x4*)vp, c = *(const LAS s16x4*)(vp + 32);
;                     bf16x8 vf; vf[0] = a[0]; vf[1] = a[1]; vf[2] = a[2]; vf[3] = a[3]; vf[4] = c[0]; vf[5] = c[1]; vf[6] = c[2]; vf[7] = c[3];
;                     O[0][nt] = mfma16(vf, Pb[0][kk], O[0][nt]); O[1][nt] = mfma16(vf, Pb[1][kk], O[1][nt]); }
	v_add3_u32 v248, s27, v96, v148
	v_add_u32_e32 v249, 0x3000, v248
	v_add_u32_e32 v250, 0x3800, v248
	v_add_u32_e32 v251, 0x4000, v248
	v_add_u32_e32 v252, 0x4800, v248
	ds_read2_b64 v[200:203], v249 offset0:128 offset1:132
	ds_read2_b64 v[204:207], v249 offset0:136 offset1:140
	ds_read2_b64 v[208:211], v250 offset0:160 offset1:164
	ds_read2_b64 v[212:215], v250 offset0:168 offset1:172
	ds_read2_b64 v[216:219], v251 offset0:192 offset1:196
	ds_read2_b64 v[220:223], v251 offset0:200 offset1:204
	ds_read2_b64 v[224:227], v252 offset0:224 offset1:228
	ds_read2_b64 v[228:231], v252 offset0:232 offset1:236
	v_max_f32_e32 v137, v137, v137
	v_max_f32_e32 v125, v125, v137
	v_mov_b32_e32 v137, v125
	s_nop 1
	v_permlane32_swap_b32_e32 v125, v137
	v_max3_f32 v125, v24, v125, v137
	v_sub_f32_e32 v24, v24, v125
	v_exp_f32_e32 v137, v24
	v_sub_f32_e32 v24, v80, v125
	v_exp_f32_e32 v139, v24
	v_sub_f32_e32 v24, v81, v125
	v_exp_f32_e32 v141, v24
	v_sub_f32_e32 v24, v82, v125
	v_exp_f32_e32 v155, v24
	v_sub_f32_e32 v24, v83, v125
	v_exp_f32_e32 v156, v72
	v_sub_f32_e32 v72, v158, v123
	v_exp_f32_e32 v157, v24
	v_sub_f32_e32 v24, v84, v125
	v_exp_f32_e32 v158, v72
	v_sub_f32_e32 v72, v159, v123
	v_exp_f32_e32 v159, v24
	v_sub_f32_e32 v24, v85, v125
	v_exp_f32_e32 v162, v72
	v_sub_f32_e32 v72, v160, v123
	v_exp_f32_e32 v163, v24
	v_sub_f32_e32 v24, v86, v125
	v_exp_f32_e32 v160, v72
	v_sub_f32_e32 v72, v161, v123
	v_exp_f32_e32 v161, v24
	v_sub_f32_e32 v24, v87, v125
	v_exp_f32_e32 v186, v72
	v_sub_f32_e32 v72, v178, v123
	v_exp_f32_e32 v187, v24
	v_sub_f32_e32 v24, v88, v125
	v_exp_f32_e32 v178, v72
	v_sub_f32_e32 v72, v179, v123
	v_exp_f32_e32 v179, v24
	v_sub_f32_e32 v24, v89, v125
	v_exp_f32_e32 v188, v72
	v_sub_f32_e32 v72, v180, v123
	v_exp_f32_e32 v189, v24
	v_sub_f32_e32 v24, v90, v125
	v_exp_f32_e32 v180, v72
	v_sub_f32_e32 v72, v181, v123
	v_exp_f32_e32 v181, v24
	v_sub_f32_e32 v24, v91, v125
	v_exp_f32_e32 v190, v72
	v_sub_f32_e32 v72, v182, v123
	v_exp_f32_e32 v191, v24
	v_sub_f32_e32 v24, v92, v125
	v_exp_f32_e32 v182, v72
	v_sub_f32_e32 v72, v183, v123
	v_exp_f32_e32 v183, v24
	v_sub_f32_e32 v24, v93, v125
	v_exp_f32_e32 v192, v72
	v_sub_f32_e32 v72, v184, v123
	v_exp_f32_e32 v193, v24
	v_sub_f32_e32 v24, v94, v125
	v_exp_f32_e32 v184, v72
	v_sub_f32_e32 v72, v185, v123
	v_exp_f32_e32 v185, v24
	v_sub_f32_e32 v24, v95, v125
	v_exp_f32_e32 v195, v24
	v_mov_b32_e32 v24, v137
	v_pk_mul_f32 v[6:7], v[6:7], v[24:25] op_sel_hi:[1,0]
	v_pk_mul_f32 v[4:5], v[4:5], v[24:25] op_sel_hi:[1,0]
	v_pk_mul_f32 v[2:3], v[2:3], v[24:25] op_sel_hi:[1,0]
	v_pk_mul_f32 v[0:1], v[0:1], v[24:25] op_sel_hi:[1,0]
	v_pk_mul_f32 v[10:11], v[10:11], v[24:25] op_sel_hi:[1,0]
	v_pk_mul_f32 v[8:9], v[8:9], v[24:25] op_sel_hi:[1,0]
	v_pk_mul_f32 v[14:15], v[14:15], v[24:25] op_sel_hi:[1,0]
	v_pk_mul_f32 v[12:13], v[12:13], v[24:25] op_sel_hi:[1,0]
	v_add3_u32 v24, s27, v96, v148
	v_add_u32_e32 v92, 0x3000, v24
	v_pk_add_f32 v[80:81], v[138:139], 0 op_sel_hi:[1,0]
	v_cvt_pk_bf16_f32 v76, v138, v140
	v_pk_add_f32 v[80:81], v[140:141], v[80:81]
	v_cvt_pk_bf16_f32 v77, v154, v156
	v_pk_add_f32 v[80:81], v[154:155], v[80:81]
	v_cvt_pk_bf16_f32 v78, v158, v162
	v_pk_add_f32 v[80:81], v[156:157], v[80:81]
	v_cvt_pk_bf16_f32 v79, v160, v186
	v_pk_add_f32 v[80:81], v[158:159], v[80:81]
	v_cvt_pk_bf16_f32 v84, v139, v141
	v_pk_add_f32 v[80:81], v[162:163], v[80:81]
	v_cvt_pk_bf16_f32 v85, v155, v157
	v_pk_add_f32 v[80:81], v[160:161], v[80:81]
	v_cvt_pk_bf16_f32 v86, v159, v163
	v_pk_add_f32 v[80:81], v[186:187], v[80:81]
	v_cvt_pk_bf16_f32 v87, v161, v187
	v_pk_add_f32 v[80:81], v[178:179], v[80:81]
	s_waitcnt lgkmcnt(0)
	v_mfma_f32_16x16x32_bf16 v[44:47], v[200:203], v[76:79], v[44:47]
	v_add_f32_e64 v80, v188, v80
	v_add_f32_e64 v81, v189, v81
	v_exp_f32_e32 v194, v72
	v_pk_add_f32 v[80:81], v[180:181], v[80:81]
	v_mfma_f32_16x16x32_bf16 v[4:7], v[200:203], v[84:87], v[4:7]
	v_pk_add_f32 v[80:81], v[190:191], v[80:81]
	v_cvt_pk_bf16_f32 v72, v178, v188
	v_pk_add_f32 v[80:81], v[182:183], v[80:81]
	v_cvt_pk_bf16_f32 v73, v180, v190
	v_pk_add_f32 v[80:81], v[192:193], v[80:81]
	v_cvt_pk_bf16_f32 v74, v182, v192
	v_pk_add_f32 v[80:81], v[184:185], v[80:81]
	v_cvt_pk_bf16_f32 v75, v184, v194
	v_pk_add_f32 v[80:81], v[194:195], v[80:81]
	v_cvt_pk_bf16_f32 v82, v183, v193
	v_pk_fma_f32 v[130:131], v[130:131], v[136:137], v[80:81]
	v_cvt_pk_bf16_f32 v80, v179, v189
	v_cvt_pk_bf16_f32 v81, v181, v191
	v_cvt_pk_bf16_f32 v83, v185, v195
	v_add_u32_e32 v92, 0x3800, v24
	s_waitcnt lgkmcnt(0)
	v_mfma_f32_16x16x32_bf16 v[44:47], v[204:207], v[72:75], v[44:47]
	v_mfma_f32_16x16x32_bf16 v[4:7], v[204:207], v[80:83], v[4:7]
	s_waitcnt lgkmcnt(0)
	v_mfma_f32_16x16x32_bf16 v[52:55], v[208:211], v[76:79], v[52:55]
	v_mfma_f32_16x16x32_bf16 v[0:3], v[208:211], v[84:87], v[0:3]
	v_add_u32_e32 v92, 0x4000, v24
	v_add_u32_e32 v24, 0x4800, v24
	s_waitcnt lgkmcnt(0)
	v_mfma_f32_16x16x32_bf16 v[52:55], v[212:215], v[72:75], v[52:55]
	v_mfma_f32_16x16x32_bf16 v[0:3], v[212:215], v[80:83], v[0:3]
	s_waitcnt lgkmcnt(0)
	v_mfma_f32_16x16x32_bf16 v[56:59], v[216:219], v[76:79], v[56:59]
	v_mfma_f32_16x16x32_bf16 v[8:11], v[216:219], v[84:87], v[8:11]
	s_waitcnt lgkmcnt(0)
	v_mfma_f32_16x16x32_bf16 v[56:59], v[220:223], v[72:75], v[56:59]
	v_mfma_f32_16x16x32_bf16 v[8:11], v[220:223], v[80:83], v[8:11]
	s_waitcnt lgkmcnt(0)
	v_mfma_f32_16x16x32_bf16 v[68:71], v[224:227], v[76:79], v[68:71]
	v_mov_b32_e32 v24, v125
	v_mfma_f32_16x16x32_bf16 v[12:15], v[224:227], v[84:87], v[12:15]
	s_waitcnt lgkmcnt(0)
	v_mfma_f32_16x16x32_bf16 v[68:71], v[228:231], v[72:75], v[68:71]
	v_mov_b32_e32 v72, v123
	v_mfma_f32_16x16x32_bf16 v[12:15], v[228:231], v[80:83], v[12:15]
